# fix-up units in quarters (one 16-row batch per ticket) instead of halves
# speedup vs baseline: 1.0086x; 1.0086x over previous
;     ...
;     unsigned* ctr = (unsigned*)(p.ws + WS_CTR) + ctr_off;
;     for (;;) {
;         const unsigned idx = wq_next(ctr, lds);
;         if (idx >= (unsigned)(MS + LRU_NCHUNK)) break;
;         if (idx < (unsigned)MS) sample_row_unit(p, lds, (int)idx); else lru_fixup_unit(p, (int)idx - MS);
.LBB0_2885:
	s_add_u32 s6, s34, 0x8000
	s_addc_u32 s7, s35, 0
	s_add_u32 s8, s34, 0x33f42200
	s_addc_u32 s9, s35, 0
	s_add_u32 s10, s34, 0x33fc4200
	s_addc_u32 s11, s35, 0
	s_add_u32 s3, s30, 0x6306000
	s_addc_u32 s23, s31, 0
	s_add_u32 s33, s34, 0x344c6200
	s_addc_u32 s46, s35, 0
	s_add_u32 s47, s34, 0x3371a000
	s_addc_u32 s48, s35, 0
	s_add_u32 s12, s30, 0x6308000
	s_addc_u32 s13, s31, 0
	s_add_u32 s14, s30, 0x6348000
	s_addc_u32 s15, s31, 0
	s_add_u32 s16, s34, 0x33fc6200
	v_writelane_b32 v239, s16, 18
	s_addc_u32 s16, s35, 0
	s_add_i32 s51, 0, 0x20c40
	s_waitcnt vmcnt(0)
	v_mbcnt_lo_u32_b32 v2, -1, 0
	s_mov_b64 s[4:5], 0x8000
	s_mov_b32 s17, 0
	v_mov_b32_e32 v11, 0
	v_mov_b32_e32 v1, s51
	s_movk_i32 s77, 0x287
	s_mov_b64 s[18:19], 0x10000
	s_mov_b64 s[36:37], 0x1000
	s_mov_b32 s88, 0x23093000
	s_mov_b32 s89, 0x23095000
	s_mov_b32 s91, 0x23097000
	s_mov_b32 s94, 0x23099000
	s_mov_b32 s95, 0x2309b000
	s_mov_b32 s96, 0x2309d000
	s_mov_b32 s97, 0x2309f000
	s_mov_b32 s49, 0x230a0000
	s_movk_i32 s50, 0x100
	s_movk_i32 s68, 0x1fff
	s_add_i32 s69, 0, 0x8600
	s_mov_b64 s[38:39], 0x80
	s_add_i32 s70, 0, 0x8a00
	s_mov_b32 s71, 0xff800000
	s_mov_b32 s72, 0x3fb8aa3b
	s_mov_b32 s73, 0xc2ce8ed0
	s_mov_b32 s74, 0x42b17218
	s_add_i32 s75, 0, 0x9600
	s_add_i32 s76, 0, 0xbe00
	v_mbcnt_hi_u32_b32 v78, -1, v2
	v_mov_b32_e32 v79, 0x7f800000
	v_writelane_b32 v238, s16, 3
	s_branch .LBB0_2889

; __device__ __forceinline__ int fresh_tid() { int t = threadIdx.x; asm volatile("" : "+v"(t)); return t; }
; __device__ __forceinline__ void lru_fixup_unit(const Params& p, int ck) {
;     const int tid = fresh_tid(), ch = tid * 2;
;     unsigned char* ws = p.ws;
;     const bf16_t* GG = (const bf16_t*)(ws + WS_GG);
;     const float* HL = (const float*)(ws + WS_HL); const float* PP = (const float*)(ws + WS_PP); const float* SUMA = (const float*)(ws + WS_SUMA); const float* SUMH = (const float*)(ws + WS_SUMH);
;     bf16_t* CATB = (bf16_t*)(ws + WS_CATB); float* PS = (float*)(ws + WS_PS);
;     typedef float f32x2 __attribute__((ext_vector_type(2)));
;     f32x2 carry = (f32x2){0.f, 0.f};
;     const bool prompt = ck < LRU_PCHUNK;
;     if (prompt) {
;         const int b = ck / LRU_CPB, kk = ck % LRU_CPB;
; #pragma unroll 16
;         for (int j = 0; j < kk; ++j) {
;             const f32x2 A = *(const f32x2*)(SUMA + (size_t)(b * LRU_CPB + j) * DRNN + ch), Hh = *(const f32x2*)(SUMH + (size_t)(b * LRU_CPB + j) * DRNN + ch);
;             carry = A * carry + Hh;
;         }
;     }
;     ...
;         const unsigned idx = wq_next(ctr, lds);
;         if (idx >= (unsigned)(MS + LRU_NCHUNK)) break;
;         if (idx < (unsigned)MS) sample_row_unit(p, lds, (int)idx); else lru_fixup_unit(p, (int)idx - MS);
.LBB0_2893:
	s_or_b64 exec, exec, s[40:41]
	s_waitcnt lgkmcnt(0)
	s_barrier
	ds_read_b32 v2, v1
	s_mov_b64 s[40:41], -1
	s_waitcnt lgkmcnt(0)
	v_cmp_lt_u32_e32 vcc, s77, v2
	v_readfirstlane_b32 s44, v2
	s_cbranch_vccnz .LBB0_2888
	s_cmpk_gt_u32 s44, 0x7f
	s_cbranch_scc0 .LBB0_2910
	v_mov_b32_e32 v2, v0
	s_add_i32 s40, s44, 0xffffff80
	s_and_b32 s45, s40, 3
	s_lshr_b32 s40, s40, 2
	s_cmpk_gt_u32 s40, 0x7f
	v_lshlrev_b32_e32 v6, 1, v2
	v_mov_b32_e32 v2, 0
	v_mov_b32_e32 v3, 0
	s_cbranch_scc1 .LBB0_2905
	s_and_b32 s16, s40, 63
	s_cmp_eq_u32 s16, 0
	s_cbranch_scc1 .LBB0_2905
	s_and_b32 s41, s40, 64
	s_lshl_b32 s41, s41, 12
	s_add_u32 s78, s8, s41
	s_addc_u32 s79, s9, 0
	s_add_u32 s42, s10, s41
	s_addc_u32 s43, s11, 0
	v_lshlrev_b32_e32 v4, 2, v6

; __device__ __forceinline__ unsigned cvt_pk_bf16(float lo, float hi) { unsigned r; asm volatile("v_cvt_pk_bf16_f32 %0, %1, %2" : "=v"(r) : "v"(lo), "v"(hi)); return r; }
; __device__ __forceinline__ unsigned cvt_pk_bf16(float lo, float hi) { unsigned r; asm volatile("v_cvt_pk_bf16_f32 %0, %1, %2" : "=v"(r) : "v"(lo), "v"(hi)); return r; }
; __device__ __forceinline__ float gelu_tanh(float x) { const float a = -2.3022081985f * (x + 0.044715f * x * x * x); return x * __builtin_amdgcn_rcpf(1.0f + __builtin_amdgcn_exp2f(a)); }
; __device__ __forceinline__ void lru_fixup_unit(const Params& p, int ck) {
;     ...
;     const bool prompt = ck < LRU_PCHUNK;
;     if (prompt) {
;         const int b = ck / LRU_CPB, kk = ck % LRU_CPB;
; #pragma unroll 16
;         for (int j = 0; j < kk; ++j) {
;             const f32x2 A = *(const f32x2*)(SUMA + (size_t)(b * LRU_CPB + j) * DRNN + ch), Hh = *(const f32x2*)(SUMH + (size_t)(b * LRU_CPB + j) * DRNN + ch);
;             carry = A * carry + Hh;
;         }
;     }
; #pragma unroll 1
;     for (int lr0 = 0; lr0 < LRU_CH; lr0 += 16) {
;         f32x2 hl[16], pp[16]; unsigned ggw[16];
; #pragma unroll
;         for (int i = 0; i < 16; ++i) { const size_t grow = (size_t)(ck * LRU_CH + lr0 + i); hl[i] = *(const f32x2*)(HL + grow * DRNN + ch); pp[i] = *(const f32x2*)(PP + grow * DRNN + ch); ggw[i] = *(const unsigned*)(GG + grow * DRNN + ch); }
; #pragma unroll
;         for (int i = 0; i < 16; ++i) {
;             const int lr = lr0 + i; const size_t grow = (size_t)(ck * LRU_CH + lr);
;             const f32x2 gg = (f32x2){gelu_tanh(__uint_as_float(ggw[i] << 16)), gelu_tanh(__uint_as_float(ggw[i] & 0xffff0000u))};
;             const f32x2 h = hl[i] + pp[i] * carry;
;             *(unsigned*)(CATB + grow * D + ch) = cvt_pk_bf16(h.x * gg.x, h.y * gg.y);
;             if (prompt && (ck % LRU_CPB) == LRU_CPB - 1 && lr == LRU_CH - 1) *(f32x2*)(p.out + O_HP + (size_t)(ck / LRU_CPB) * DRNN + ch) = h;
;         }
.LBB0_2905:
	s_lshl_b32 s16, s40, 17
	s_and_b32 s41, s40, 0xbf
	s_cmp_eq_u32 s41, 63
	s_cselect_b64 s[42:43], -1, 0
	s_lshl_b32 s78, s40, 16
	s_lshl_b32 s40, s40, 6
	s_and_b32 s40, s40, 0x1000
	v_ashrrev_i32_e32 v7, 31, v6
	s_add_u32 s40, s3, s40
	s_addc_u32 s41, s23, 0
	v_lshlrev_b64 v[8:9], 2, v[6:7]
	v_lshlrev_b64 v[12:13], 1, v[6:7]
	s_mov_b32 s79, s17
	v_lshl_add_u64 v[4:5], s[40:41], 0, v[8:9]
	v_lshl_add_u64 v[6:7], s[16:17], 1, v[12:13]
	v_lshl_add_u64 v[8:9], s[78:79], 2, v[8:9]
	v_lshl_add_u64 v[12:13], v[12:13], 0, s[16:17]
	s_lshl_b32 s78, s45, 16
	s_mov_b32 s79, 0
	v_lshl_add_u64 v[6:7], v[6:7], 0, s[78:79]
	v_lshl_add_u64 v[8:9], v[8:9], 0, s[78:79]
	s_lshl_b32 s78, s45, 15
	v_lshl_add_u64 v[12:13], v[12:13], 0, s[78:79]
	s_lshl_b32 s16, s45, 4
	s_add_i32 s16, s16, -16
	s_xor_b64 s[40:41], s[42:43], -1
	s_branch .LBB0_2907
.LBB0_2906:
	s_add_i32 s16, s16, 16
	v_lshl_add_u64 v[6:7], v[6:7], 0, s[18:19]
	v_lshl_add_u64 v[8:9], v[8:9], 0, s[18:19]
	s_lshl_b32 s78, s45, 4
	s_add_i32 s78, s78, -1
	s_cmp_gt_i32 s16, s78
	v_lshl_add_u64 v[12:13], v[12:13], 0, s[4:5]
	s_cbranch_scc1 .LBB0_2909
